# attention loop: step-B QK writes scores directly (no v_mov/s_nop), LDS fragment prefetch 2 pairs ahead, exps interleaved into QK MFMA gaps, negm read as MFMA C from v48-63, waves 4-7 setprio 1
# baseline (speedup 1.0000x reference)
; #define AT_LOADK(kt) do { kA = *(const u32x4*)(kp0 + (size_t)(kt) * ks0); if (tid < 256) kB = *(const u32x4*)(kp1 + (size_t)(kt) * ks1); } while (0)
; #define AT_LOADV(kt) do { vR = *(const u32x4*)(vp0 + (kt) * 64); } while (0)
; #define AT_STOREK(bi) do { bf16_t* Kw_ = (bf16_t*)(lds + (bi) * AT_KB); *(u32x4*)(Kw_ + key0 * AK + part0 * 8) = kA; if (tid < 256) *(u32x4*)(Kw_ + key1 * AK + part1 * 8) = kB; } while (0)
; #define AT_STOREV(bi) do { bf16_t* Vw_ = (bf16_t*)(lds + 2 * AT_KB + (bi) * AT_VB); *(u32x4*)(Vw_ + ve * AV + vpart * 8) = vR; } while (0)
; #define AT_QK(P0, P1, bi, CI) do { const bf16_t* Kt_ = (const bf16_t*)(lds + (bi) * AT_KB); P0 = CI; P1 = CI; \
;         _Pragma("unroll") for (int s = 0; s < 6; ++s) { const bf16x8 a0_ = *(const bf16x8*)(Kt_ + r32 * AK + 16 * s + 8 * hi), a1_ = *(const bf16x8*)(Kt_ + (32 + r32) * AK + 16 * s + 8 * hi); \
;             P0 = MFMA32(a0_, qr[s], P0); P1 = MFMA32(a1_, qr[s], P1); } } while (0)
; __device__ __forceinline__ void attn_unit(const Params& P, unsigned char* lds, int b, int h, int qb, int tid) {
;     ...
;     float mref, l_part = 0.f;
;     f32x16 o0, o1, negm, sa0, sa1, sb0, sb1;
; #pragma unroll
;     for (int i = 0; i < 16; ++i) { o0[i] = 0.f; o1[i] = 0.f; negm[i] = 0.f; }
;     AT_LOADK(0); AT_LOADV(0); AT_STOREK(0); AT_STOREV(0); AT_LOADK(1);
;     __syncthreads();
;     AT_QK(sa0, sa1, 0, negm);
;     { float mx = fmaxf(sa0[0], sa1[0]);
; #pragma unroll
;       for (int i = 1; i < 16; ++i) mx = fmaxf(mx, fmaxf(sa0[i], sa1[i]));
;       { auto rr_ = __builtin_amdgcn_permlane32_swap(__float_as_uint(mx), __float_as_uint(mx), false, false); mx = fmaxf(__uint_as_float(rr_[0]), __uint_as_float(rr_[1])); }
;       mref = mx;
; #pragma unroll
;       for (int i = 0; i < 16; ++i) { sa0[i] -= mx; sa1[i] -= mx; negm[i] = -mx; } }
;     AT_STOREK(1); AT_LOADK(2); AT_LOADV(1);
;     __syncthreads();
.LBB0_168:
	s_or_b64 exec, exec, s[10:11]
	s_mov_b64 s[10:11], 0xac00000
	v_lshl_add_u64 v[46:47], v[36:37], 0, s[10:11]
	global_load_dwordx4 v[144:147], v[46:47], off offset:128
	v_max_f32_e32 v32, v44, v44
	v_max_f32_e32 v33, v42, v42
	v_max_f32_e32 v225, v33, v32
	v_sub_f32_e32 v182, v0, v225
	v_and_b32_e32 v0, 0x3fffffc0, v49
	v_lshl_add_u32 v226, v0, 2, 0
	v_lshlrev_b32_e32 v0, 6, v222
	v_sub_u32_e32 v0, v56, v0
	v_lshl_add_u32 v229, v64, 1, v0
	v_and_b32_e32 v0, 7, v49
	v_sub_f32_e32 v183, v1, v225
	v_lshlrev_b32_e32 v0, 4, v0
	v_mov_b32_e32 v1, v153
	v_sub_f32_e32 v184, v2, v225
	v_sub_f32_e32 v185, v3, v225
	v_lshl_add_u64 v[0:1], v[52:53], 0, v[0:1]
	v_add_u32_e32 v2, v51, v54
	v_mov_b32_e32 v3, v153
	v_lshl_add_u64 v[0:1], v[2:3], 1, v[0:1]
	v_sub_f32_e32 v196, v14, v225
	v_sub_f32_e32 v197, v15, v225
	v_lshl_add_u64 v[0:1], s[12:13], 0, v[0:1]
	s_mov_b64 s[10:11], 0xac00180
	v_mov_b32_e32 v14, v153
	v_mov_b32_e32 v15, v153
	v_xor_b32_e32 v48, 0x80000000, v225
	v_sub_f32_e32 v32, v16, v225
	v_sub_f32_e32 v33, v17, v225
	v_sub_f32_e32 v34, v18, v225
	v_sub_f32_e32 v35, v19, v225
	v_sub_f32_e32 v36, v20, v225
	v_sub_f32_e32 v37, v21, v225
	v_sub_f32_e32 v38, v22, v225
	v_sub_f32_e32 v39, v23, v225
	v_sub_f32_e32 v40, v24, v225
	v_sub_f32_e32 v41, v25, v225
	v_sub_f32_e32 v42, v26, v225
	v_sub_f32_e32 v43, v27, v225
	v_sub_f32_e32 v44, v28, v225
	v_sub_f32_e32 v45, v29, v225
	v_sub_f32_e32 v46, v30, v225
	v_sub_f32_e32 v47, v31, v225
	v_sub_f32_e32 v186, v4, v225
	v_sub_f32_e32 v187, v5, v225
	v_sub_f32_e32 v188, v6, v225
	v_sub_f32_e32 v189, v7, v225
	v_sub_f32_e32 v190, v8, v225
	v_sub_f32_e32 v191, v9, v225
	v_sub_f32_e32 v192, v10, v225
	v_sub_f32_e32 v193, v11, v225
	v_sub_f32_e32 v194, v12, v225
	v_sub_f32_e32 v195, v13, v225
	v_lshl_add_u64 v[176:177], v[0:1], 0, s[10:11]
	v_mov_b32_e32 v0, v153
	v_mov_b32_e32 v1, v153
	v_mov_b32_e32 v2, v153
	v_mov_b32_e32 v4, v153
	v_mov_b32_e32 v5, v153
	v_mov_b32_e32 v6, v153
	v_mov_b32_e32 v7, v153
	v_mov_b32_e32 v8, v153
	v_mov_b32_e32 v9, v153
	v_mov_b32_e32 v10, v153
	v_mov_b32_e32 v11, v153
	v_mov_b32_e32 v12, v153
	v_mov_b32_e32 v13, v153
	v_mov_b64_e32 v[30:31], v[14:15]
	v_add_u32_e32 v228, 0, v55
	v_cndmask_b32_e64 v174, 11, 16, s[8:9]
	v_cmp_eq_u32_e64 s[8:9], 0, v223
	v_lshl_add_u32 v227, v222, 2, v226
	v_lshlrev_b32_e32 v178, 3, v50
	v_mov_b32_e32 v179, v153
	v_mul_hi_u32_u24_e32 v181, 6, v50
	v_mul_u32_u24_e32 v180, 6, v50
	v_mov_b32_e32 v230, 0
	s_mov_b64 s[92:93], 4
	v_mov_b64_e32 v[28:29], v[12:13]
	v_mov_b64_e32 v[26:27], v[10:11]
	v_mov_b64_e32 v[24:25], v[8:9]
	v_mov_b64_e32 v[22:23], v[6:7]
	v_mov_b64_e32 v[20:21], v[4:5]
	v_mov_b64_e32 v[18:19], v[2:3]
	v_mov_b64_e32 v[16:17], v[0:1]
	v_mov_b32_e32 v49, v48
	v_mov_b32_e32 v50, v48
	v_mov_b32_e32 v51, v48
	v_mov_b32_e32 v52, v48
	v_mov_b32_e32 v53, v48
	v_mov_b32_e32 v54, v48
	v_mov_b32_e32 v55, v48
	v_mov_b32_e32 v56, v48
	v_mov_b32_e32 v57, v48
	v_mov_b32_e32 v58, v48
	v_mov_b32_e32 v59, v48
	v_mov_b32_e32 v60, v48
	v_mov_b32_e32 v61, v48
	v_mov_b32_e32 v62, v48
	v_mov_b32_e32 v63, v48
	v_readfirstlane_b32 s10, v217
	s_cmpk_lt_u32 s10, 0x100
	s_cbranch_scc1 .Latt_noprio
	s_setprio 1
.Latt_noprio:
	s_waitcnt lgkmcnt(0)
	s_barrier
	s_branch .LBB0_170
.LBB0_169:
	v_exp_f32_e32 v72, v80
	v_exp_f32_e32 v96, v96
	v_exp_f32_e32 v150, v97
	v_exp_f32_e32 v73, v82
	v_exp_f32_e32 v97, v98
	v_exp_f32_e32 v74, v81
	v_exp_f32_e32 v75, v83
	v_exp_f32_e32 v151, v99
	v_exp_f32_e32 v76, v84
	v_exp_f32_e32 v98, v100
	v_exp_f32_e32 v77, v86
	v_exp_f32_e32 v99, v102
	v_exp_f32_e32 v78, v85
	v_exp_f32_e32 v100, v101
	v_exp_f32_e32 v79, v87
	v_exp_f32_e32 v101, v103
	v_exp_f32_e32 v88, v88
	v_exp_f32_e32 v64, v104
	v_exp_f32_e32 v102, v89
	v_exp_f32_e32 v89, v90
	v_exp_f32_e32 v65, v106
	v_exp_f32_e32 v66, v105
	v_exp_f32_e32 v103, v91
	v_exp_f32_e32 v67, v107
	v_exp_f32_e32 v90, v92
	v_exp_f32_e32 v68, v108
	v_exp_f32_e32 v91, v94
	v_exp_f32_e32 v69, v110
	v_exp_f32_e32 v92, v93
	v_exp_f32_e32 v70, v109
	v_exp_f32_e32 v93, v95
	v_exp_f32_e32 v71, v111
.Latt_b_tail:
	v_pk_add_f32 v[80:81], v[96:97], v[72:73]
	v_pk_add_f32 v[80:81], v[80:81], 0 op_sel_hi:[1,0]
	v_pk_add_f32 v[82:83], v[150:151], v[74:75]
	v_pk_add_f32 v[84:85], v[98:99], v[76:77]
	v_pk_add_f32 v[82:83], v[82:83], 0 op_sel_hi:[1,0]
	v_pk_add_f32 v[80:81], v[84:85], v[80:81]
	v_pk_add_f32 v[84:85], v[100:101], v[78:79]
	s_mov_b64 s[10:11], 0x100
	v_pk_add_f32 v[82:83], v[84:85], v[82:83]
	v_pk_add_f32 v[84:85], v[64:65], v[88:89]
	s_add_u32 s92, s92, 2
	v_pk_add_f32 v[80:81], v[84:85], v[80:81]
	v_pk_add_f32 v[84:85], v[66:67], v[102:103]
	v_lshl_add_u64 v[176:177], v[176:177], 0, s[10:11]
	v_pk_add_f32 v[82:83], v[84:85], v[82:83]
	v_pk_add_f32 v[84:85], v[68:69], v[90:91]
	s_addc_u32 s93, s93, 0
	v_pk_add_f32 v[80:81], v[84:85], v[80:81]
	v_pk_add_f32 v[84:85], v[70:71], v[92:93]
	v_cvt_pk_bf16_f32 v72, v72, v74
	v_pk_add_f32 v[82:83], v[84:85], v[82:83]
	v_cvt_pk_bf16_f32 v73, v73, v75
	v_pk_add_f32 v[80:81], v[80:81], v[82:83]
	s_add_i32 s10, s92, -6
	v_add_f32_e32 v94, v80, v81
	ds_read_b128 v[80:83], v229 offset:35840
	ds_read_b128 v[84:87], v229 offset:35872
	v_cvt_pk_bf16_f32 v74, v76, v78
	v_cvt_pk_bf16_f32 v75, v77, v79
	v_cvt_pk_bf16_f32 v64, v64, v66
	v_cvt_pk_bf16_f32 v65, v65, v67
	v_cvt_pk_bf16_f32 v66, v68, v70
	s_waitcnt lgkmcnt(1)
	v_mfma_f32_32x32x16_bf16 v[0:15], v[72:75], v[80:83], v[0:15]
	ds_read_b128 v[76:79], v229 offset:40448
	ds_read_b128 v[80:83], v229 offset:40512
	v_cvt_pk_bf16_f32 v67, v69, v71
	v_add_f32_e32 v230, v148, v94
	v_lshl_add_u64 v[170:171], v[170:171], 0, v[172:173]
	s_cmp_gt_u32 s10, 61
	s_waitcnt lgkmcnt(1)
	v_mfma_f32_32x32x16_bf16 v[16:31], v[72:75], v[76:79], v[16:31]
	ds_read_b128 v[76:79], v229 offset:40480
	ds_read_b128 v[68:71], v229 offset:35936
	v_cvt_pk_bf16_f32 v72, v88, v102
	v_cvt_pk_bf16_f32 v73, v89, v103
	v_cvt_pk_bf16_f32 v74, v90, v92
	v_cvt_pk_bf16_f32 v75, v91, v93
	s_nop 1
	v_mfma_f32_32x32x16_bf16 v[0:15], v[72:75], v[84:87], v[0:15]
	s_waitcnt lgkmcnt(1)
	v_mfma_f32_32x32x16_bf16 v[16:31], v[72:75], v[76:79], v[16:31]
	ds_read_b128 v[76:79], v229 offset:35904
	v_cvt_pk_bf16_f32 v72, v96, v150
	v_cvt_pk_bf16_f32 v73, v97, v151
	v_cvt_pk_bf16_f32 v74, v98, v100
	v_cvt_pk_bf16_f32 v75, v99, v101
	s_waitcnt lgkmcnt(0)
	s_nop 0
	v_mfma_f32_32x32x16_bf16 v[0:15], v[72:75], v[76:79], v[0:15]
	v_mfma_f32_32x32x16_bf16 v[16:31], v[72:75], v[80:83], v[16:31]
	ds_read_b128 v[72:75], v229 offset:40544
	s_waitcnt lgkmcnt(0)
	s_barrier
	v_mfma_f32_32x32x16_bf16 v[16:31], v[64:67], v[72:75], v[16:31]
	v_mfma_f32_32x32x16_bf16 v[0:15], v[64:67], v[68:71], v[0:15]
	s_cbranch_scc1 .LBB0_203

.LBB0_180:
	v_max3_f32 v64, v32, v33, v182
	v_max3_f32 v65, v34, v35, v183
	v_max3_f32 v64, v64, v184, v185
	v_max3_f32 v65, v65, v38, v39
	v_max3_f32 v64, v64, v36, v37
	v_max3_f32 v65, v65, v188, v189
	v_max3_f32 v64, v64, v186, v187
	v_max3_f32 v65, v65, v42, v43
	v_max3_f32 v64, v64, v40, v41
	v_max3_f32 v65, v65, v192, v193
	v_max3_f32 v64, v64, v190, v191
	v_max3_f32 v65, v65, v46, v47
	v_max3_f32 v64, v64, v44, v45
	v_max3_f32 v65, v65, v196, v197
	v_max3_f32 v64, v64, v194, v195
	s_nop 0
	v_max_f32_e32 v64, v64, v65
	s_nop 0
	v_mov_b32_e32 v65, v64
	s_nop 1
	v_permlane32_swap_b32_e32 v64, v65
	v_max_f32_e32 v64, v64, v65
	s_nop 0
	v_cmp_lt_f32_e32 vcc, s55, v64
	s_cbranch_vccnz .LBB0_197
.LBB0_182:
	ds_read_b128 v[96:99], v169 offset:13312
	ds_read_b128 v[232:235], v169 offset:19968
	v_exp_f32_e32 v32, v32
	v_exp_f32_e32 v33, v33
	v_exp_f32_e32 v34, v34
	v_exp_f32_e32 v35, v35
	v_exp_f32_e32 v36, v36
	v_exp_f32_e32 v37, v37
	v_exp_f32_e32 v38, v38
	s_waitcnt lgkmcnt(1)
	v_mfma_f32_32x32x16_bf16 v[80:95], v[96:99], v[116:119], v[48:63]
	ds_read_b128 v[100:103], v169 offset:13344
	ds_read_b128 v[236:239], v169 offset:20000
	v_exp_f32_e32 v39, v39
	v_exp_f32_e32 v40, v40
	v_exp_f32_e32 v41, v41
	v_exp_f32_e32 v42, v42
	v_exp_f32_e32 v43, v43
	v_exp_f32_e32 v44, v44
	s_waitcnt lgkmcnt(1)
	v_mfma_f32_32x32x16_bf16 v[80:95], v[100:103], v[120:123], v[80:95]
	ds_read_b128 v[96:99], v169 offset:13376
	ds_read_b128 v[240:243], v169 offset:20032
	v_exp_f32_e32 v45, v45
	v_exp_f32_e32 v46, v46
	v_exp_f32_e32 v47, v47
	v_exp_f32_e32 v182, v182
	v_exp_f32_e32 v183, v183
	s_waitcnt lgkmcnt(1)
	v_mfma_f32_32x32x16_bf16 v[80:95], v[96:99], v[124:127], v[80:95]
	ds_read_b128 v[96:99], v169 offset:13408
	ds_read_b128 v[244:247], v169 offset:20064
	v_exp_f32_e32 v184, v184
	v_exp_f32_e32 v185, v185
	v_exp_f32_e32 v186, v186
	v_exp_f32_e32 v187, v187
	v_exp_f32_e32 v188, v188
	s_waitcnt lgkmcnt(1)
	v_mfma_f32_32x32x16_bf16 v[80:95], v[96:99], v[128:131], v[80:95]
	ds_read_b128 v[96:99], v169 offset:13440
	ds_read_b128 v[248:251], v169 offset:20096
	v_exp_f32_e32 v189, v189
	v_exp_f32_e32 v190, v190
	v_exp_f32_e32 v191, v191
	v_exp_f32_e32 v192, v192
	v_exp_f32_e32 v193, v193
	s_waitcnt lgkmcnt(1)
	v_mfma_f32_32x32x16_bf16 v[80:95], v[96:99], v[132:135], v[80:95]
	ds_read_b128 v[96:99], v169 offset:13472
	ds_read_b128 v[148:151], v169 offset:20128
	v_exp_f32_e32 v194, v194
	v_exp_f32_e32 v195, v195
	v_exp_f32_e32 v196, v196
	v_exp_f32_e32 v197, v197
	s_andn2_b64 vcc, exec, s[28:29]
	s_waitcnt lgkmcnt(1)
	v_mfma_f32_32x32x16_bf16 v[80:95], v[96:99], v[136:139], v[80:95]
	v_mfma_f32_32x32x16_bf16 v[96:111], v[232:235], v[116:119], v[48:63]
	v_cvt_pk_bf16_f32 v232, v32, v33
	v_cvt_pk_bf16_f32 v233, v34, v35
	v_cvt_pk_bf16_f32 v234, v36, v37
	v_cvt_pk_bf16_f32 v235, v38, v39
	v_mfma_f32_32x32x16_bf16 v[96:111], v[236:239], v[120:123], v[96:111]
	ds_read_b128 v[236:239], v229 offset:31232
	v_mfma_f32_32x32x16_bf16 v[96:111], v[240:243], v[124:127], v[96:111]
	ds_read_b128 v[240:243], v229 offset:26624
	v_mfma_f32_32x32x16_bf16 v[96:111], v[244:247], v[128:131], v[96:111]
	ds_read_b128 v[244:247], v229 offset:26656
	v_mfma_f32_32x32x16_bf16 v[96:111], v[248:251], v[132:135], v[96:111]
	s_waitcnt lgkmcnt(1)
	v_mfma_f32_32x32x16_bf16 v[0:15], v[232:235], v[240:243], v[0:15]
	ds_read_b128 v[240:243], v229 offset:31296
	v_mfma_f32_32x32x16_bf16 v[16:31], v[232:235], v[236:239], v[16:31]
	ds_read_b128 v[236:239], v229 offset:31264
	v_cvt_pk_bf16_f32 v232, v40, v41
	v_cvt_pk_bf16_f32 v233, v42, v43
	v_cvt_pk_bf16_f32 v234, v44, v45
	v_cvt_pk_bf16_f32 v235, v46, v47
	s_waitcnt lgkmcnt(2)
	s_nop 0
	v_mfma_f32_32x32x16_bf16 v[0:15], v[232:235], v[244:247], v[0:15]
	s_waitcnt lgkmcnt(0)
	v_mfma_f32_32x32x16_bf16 v[16:31], v[232:235], v[236:239], v[16:31]
	ds_read_b128 v[236:239], v229 offset:26688
	v_cvt_pk_bf16_f32 v232, v182, v183
	v_cvt_pk_bf16_f32 v233, v184, v185
	v_cvt_pk_bf16_f32 v234, v186, v187
	v_cvt_pk_bf16_f32 v235, v188, v189
	s_waitcnt lgkmcnt(0)
	s_nop 0
	v_mfma_f32_32x32x16_bf16 v[0:15], v[232:235], v[236:239], v[0:15]
	ds_read_b128 v[236:239], v229 offset:26720
	v_mfma_f32_32x32x16_bf16 v[16:31], v[232:235], v[240:243], v[16:31]
	ds_read_b128 v[240:243], v229 offset:31328
	v_cvt_pk_bf16_f32 v232, v190, v191
	v_cvt_pk_bf16_f32 v233, v192, v193
	v_cvt_pk_bf16_f32 v234, v194, v195
	v_cvt_pk_bf16_f32 v235, v196, v197
	s_waitcnt lgkmcnt(0)
	s_barrier
	v_mfma_f32_32x32x16_bf16 v[0:15], v[232:235], v[236:239], v[0:15]
	v_mfma_f32_32x32x16_bf16 v[96:111], v[148:151], v[136:139], v[96:111]
	v_cndmask_b32_e64 v148, 0, 1, s[28:29]
	v_cmp_ne_u32_e64 s[12:13], 1, v148
	v_mfma_f32_32x32x16_bf16 v[16:31], v[232:235], v[240:243], v[16:31]
	s_cbranch_vccz .LBB0_190
	s_and_b64 vcc, exec, s[10:11]
	s_cbranch_vccz .LBB0_193

.LBB0_187:
	v_add_f32_e32 v148, v182, v32
	v_add_f32_e32 v148, 0, v148
	v_add_f32_e32 v149, v183, v33
	v_add_f32_e32 v231, v186, v36
	v_add_f32_e32 v149, 0, v149
	v_add_f32_e32 v150, v184, v34
	v_add_f32_e32 v148, v231, v148
	v_add_f32_e32 v231, v187, v37
	v_add_f32_e32 v150, 0, v150
	v_add_f32_e32 v151, v185, v35
	v_add_f32_e32 v149, v231, v149
	v_add_f32_e32 v231, v188, v38
	v_add_f32_e32 v151, 0, v151
	v_add_f32_e32 v150, v231, v150
	v_add_f32_e32 v231, v189, v39
	v_add_f32_e32 v151, v231, v151
	v_add_f32_e32 v231, v190, v40
	v_add_f32_e32 v148, v231, v148
	v_add_f32_e32 v231, v191, v41
	v_add_f32_e32 v149, v231, v149
	v_add_f32_e32 v231, v192, v42
	v_add_f32_e32 v150, v231, v150
	v_add_f32_e32 v231, v193, v43
	v_add_f32_e32 v151, v231, v151
	v_add_f32_e32 v231, v194, v44
	v_add_f32_e32 v148, v231, v148
	v_add_f32_e32 v231, v195, v45
	v_add_f32_e32 v149, v231, v149
	v_add_f32_e32 v231, v196, v46
	v_add_f32_e32 v150, v231, v150
	v_add_f32_e32 v231, v197, v47
	v_add_f32_e32 v151, v231, v151
	v_add_f32_e32 v148, v148, v149
	v_add_f32_e32 v149, v150, v151
	v_add_f32_e32 v148, v148, v149
	v_max3_f32 v149, v80, v81, v96
	v_max3_f32 v150, v82, v83, v97
	v_add_f32_e32 v148, v230, v148
	v_max3_f32 v149, v149, v98, v99
	v_max3_f32 v150, v150, v86, v87
	v_max3_f32 v149, v149, v84, v85
	v_max3_f32 v150, v150, v102, v103
	v_max3_f32 v149, v149, v100, v101
	v_max3_f32 v150, v150, v90, v91
	v_max3_f32 v149, v149, v88, v89
	v_max3_f32 v150, v150, v106, v107
	v_max3_f32 v149, v149, v104, v105
	v_max3_f32 v150, v150, v94, v95
	v_max3_f32 v149, v149, v92, v93
	v_max3_f32 v150, v150, v110, v111
	v_max3_f32 v149, v149, v108, v109
	s_nop 0
	v_max_f32_e32 v149, v149, v150
	s_nop 0
	v_mov_b32_e32 v150, v149
	s_nop 1
	v_permlane32_swap_b32_e32 v149, v150
	v_max_f32_e32 v149, v149, v150
	s_nop 0
	v_cmp_lt_f32_e32 vcc, s55, v149
	s_cbranch_vccnz .LBB0_200
	s_and_b64 vcc, exec, s[10:11]
	s_cbranch_vccnz .LBB0_169
.LBB0_189:
	ds_read_b128 v[232:235], v169
	ds_read_b128 v[236:239], v169 offset:6656
	ds_read_b128 v[240:243], v169 offset:32
	ds_read_b128 v[244:247], v169 offset:6688
	ds_read_b128 v[248:251], v169 offset:64
	s_waitcnt lgkmcnt(3)
	v_mfma_f32_32x32x16_bf16 v[32:47], v[232:235], v[116:119], v[48:63]
	v_exp_f32_e32 v72, v80
	v_exp_f32_e32 v96, v96
	v_exp_f32_e32 v150, v97
	v_mfma_f32_32x32x16_bf16 v[182:197], v[236:239], v[116:119], v[48:63]
	v_exp_f32_e32 v73, v82
	v_exp_f32_e32 v97, v98
	v_exp_f32_e32 v74, v81
	ds_read_b128 v[232:235], v169 offset:6720
	ds_read_b128 v[236:239], v169 offset:96
	s_waitcnt lgkmcnt(3)
	v_mfma_f32_32x32x16_bf16 v[32:47], v[240:243], v[120:123], v[32:47]
	v_exp_f32_e32 v75, v83
	v_exp_f32_e32 v151, v99
	v_exp_f32_e32 v76, v84
	v_mfma_f32_32x32x16_bf16 v[182:197], v[244:247], v[120:123], v[182:197]
	v_exp_f32_e32 v98, v100
	v_exp_f32_e32 v77, v86
	v_exp_f32_e32 v99, v102
	ds_read_b128 v[240:243], v169 offset:6752
	ds_read_b128 v[244:247], v169 offset:128
	s_waitcnt lgkmcnt(3)
	v_mfma_f32_32x32x16_bf16 v[32:47], v[248:251], v[124:127], v[32:47]
	v_exp_f32_e32 v78, v85
	v_exp_f32_e32 v100, v101
	v_exp_f32_e32 v79, v87
	v_mfma_f32_32x32x16_bf16 v[182:197], v[232:235], v[124:127], v[182:197]
	v_exp_f32_e32 v101, v103
	v_exp_f32_e32 v88, v88
	v_exp_f32_e32 v64, v104
	ds_read_b128 v[248:251], v169 offset:6784
	ds_read_b128 v[232:235], v169 offset:160
	s_waitcnt lgkmcnt(3)
	v_mfma_f32_32x32x16_bf16 v[32:47], v[236:239], v[128:131], v[32:47]
	v_exp_f32_e32 v102, v89
	v_exp_f32_e32 v89, v90
	v_exp_f32_e32 v65, v106
	v_mfma_f32_32x32x16_bf16 v[182:197], v[240:243], v[128:131], v[182:197]
	v_exp_f32_e32 v66, v105
	v_exp_f32_e32 v103, v91
	v_exp_f32_e32 v67, v107
	ds_read_b128 v[236:239], v169 offset:6816
	s_waitcnt lgkmcnt(2)
	v_mfma_f32_32x32x16_bf16 v[32:47], v[244:247], v[132:135], v[32:47]
	v_exp_f32_e32 v90, v92
	v_exp_f32_e32 v68, v108
	v_mfma_f32_32x32x16_bf16 v[182:197], v[248:251], v[132:135], v[182:197]
	v_exp_f32_e32 v91, v94
	v_exp_f32_e32 v69, v110
	s_waitcnt lgkmcnt(0)
	v_mfma_f32_32x32x16_bf16 v[32:47], v[232:235], v[136:139], v[32:47]
	v_exp_f32_e32 v92, v93
	v_exp_f32_e32 v70, v109
	v_mfma_f32_32x32x16_bf16 v[182:197], v[236:239], v[136:139], v[182:197]
	v_exp_f32_e32 v93, v95
	v_exp_f32_e32 v71, v111
	s_branch .Latt_b_tail

; __device__ __forceinline__ float halves_pair_sum(float v) { auto r = __builtin_amdgcn_permlane32_swap(__float_as_uint(v), __float_as_uint(v), false, false); return __uint_as_float(r[0]) + __uint_as_float(r[1]); }
; __device__ __forceinline__ void attn_unit(const Params& P, unsigned char* lds, int b, int h, int qb, int tid) {
;     ...
;     float l_run = halves_pair_sum(l_part);
;     if (hi == 0) wsf[32 + r32] = l_run;
.LBB0_203:
	s_setprio 0
	v_mov_b32_e32 v32, v230
	s_nop 1
	v_permlane32_swap_b32_e32 v230, v32
	s_and_saveexec_b64 s[6:7], s[8:9]
	s_cbranch_execz .LBB0_135
	v_add_f32_e32 v32, v230, v32
	ds_write_b32 v227, v32 offset:45184
	s_branch .LBB0_135

; __device__ __forceinline__ unsigned pk_bf16_rne(float lo, float hi) { f32x2 v = {lo, hi}; bf16x2e b = __builtin_convertvector(v, bf16x2e); return __builtin_bit_cast(unsigned, b); }
; __device__ __forceinline__ float silu_f(float x) { return x * __builtin_amdgcn_rcpf(1.0f + __expf(-x)); }
;     __device__ __forceinline__ void operator()(const f32x4 (&acc)[2][2][4][2], const Unit& u, int wr, int wc, int fr, int fq) const {
; #pragma unroll
;         for (int ai = 0; ai < 2; ++ai)
; #pragma unroll
;             for (int m = 0; m < 4; ++m) {
;                 const int r = u.pm * BM + ai * HALF + wr * 64 + m * 16 + fr;
; #pragma unroll
;                 for (int bj = 0; bj < 2; ++bj) {
;                     const int cb = u.pn * BM + bj * HALF + wc * 32;
;                     const f32x4 v0 = acc[ai][bj][m][0], v1 = acc[ai][bj][m][1];
;                     if (MODE == 0) {
;                         u32x2e w; w.x = pk_bf16_rne(silu_f(v0[0]) * v1[0], silu_f(v0[1]) * v1[1]); w.y = pk_bf16_rne(silu_f(v0[2]) * v1[2], silu_f(v0[3]) * v1[3]);
;                         *(u32x2e*)(Hh + (size_t)r * ldo + (cb >> 1) + 4 * fq) = w;
;                     } else if (MODE == 1) {
;                         const int b = r >> 12;
; #pragma unroll
;                         for (int n = 0; n < 2; ++n) { const int c = cb + 16 * n + 4 * fq; const f32x4 g = *(const f32x4*)(gv + b * 9216 + c); f32x4* xp = (f32x4*)(F + (size_t)r * 1024 + c);
;                             f32x4 x = *xp; x += (n == 0 ? v0 : v1) * g * coef; *xp = x; }
;                     } else if (MODE == 2) {
;                         if (u.pn < 8) {
;                             *(f32x4*)(F + (size_t)r * 2048 + cb + 4 * fq) = v0; *(f32x4*)(F + (size_t)r * 2048 + cb + 16 + 4 * fq) = v1;
;                         } else {
;                             u32x2e w0, w1; w0.x = pk_bf16_rne(v0[0], v0[1]); w0.y = pk_bf16_rne(v0[2], v0[3]); w1.x = pk_bf16_rne(v1[0], v1[1]); w1.y = pk_bf16_rne(v1[2], v1[3]);
;                             *(u32x2e*)(Hh + (size_t)r * 1024 + (cb - 2048) + 4 * fq) = w0; *(u32x2e*)(Hh + (size_t)r * 1024 + (cb - 2048) + 16 + 4 * fq) = w1;
;                         }
.LBB0_449:
	s_lshl_b32 s25, s24, 8
	s_add_i32 s25, s25, s45
	s_ashr_i32 s4, s25, 12
	v_or_b32_e32 v138, s25, v146
	s_mul_i32 s88, s4, 0x2400
	s_lshl_b32 s4, s41, 8
	v_ashrrev_i32_e32 v139, 31, v138
	s_ashr_i32 s89, s88, 31
	s_or_b32 s86, s4, s37
	v_lshlrev_b64 v[144:145], 10, v[138:139]
	v_lshlrev_b64 v[142:143], 11, v[138:139]
	v_lshlrev_b64 v[140:141], 12, v[138:139]
	s_mov_b64 s[90:91], -1
	s_mov_b64 s[4:5], 0
	s_cmp_lt_i32 s66, 1
	s_mov_b64 s[28:29], 0
	s_cbranch_scc1 .LBB0_461
	s_cmp_gt_i32 s66, 1
	s_cbranch_scc0 .LBB0_458
	s_cmp_eq_u32 s66, 2
	s_mov_b64 s[28:29], -1
	s_cbranch_scc0 .LBB0_457
	s_cmp_gt_i32 s41, 7
	s_cbranch_scc0 .LBB0_454
	v_lshl_add_u64 v[164:165], v[144:145], 1, s[74:75]
	s_mov_b32 s87, s23
	v_lshl_add_u64 v[164:165], s[86:87], 1, v[164:165]
	v_lshlrev_b32_e32 v152, 1, v132
	v_cvt_pk_bf16_f32 v160, v124, v125
	v_cvt_pk_bf16_f32 v161, v126, v127
	v_lshl_add_u64 v[164:165], v[164:165], 0, v[152:153]
	v_cvt_pk_bf16_f32 v162, v120, v121
	v_cvt_pk_bf16_f32 v163, v122, v123
	global_store_dwordx2 v[164:165], v[160:161], off offset:-4096
	global_store_dwordx2 v[164:165], v[162:163], off offset:-4064
	s_mov_b64 s[28:29], 0
